# diff attention DMA stagger widened: waves 0-3 issue at tile start, waves 4-7 under the last PV group
# baseline (speedup 1.0000x reference)
; template <int DK, int DV, int NM, bool CAUSAL> ...
;     ...
;   for (int kt = 0; kt < nkt; ++kt) {
;     if (kt + 2 < nkt) asm volatile("s_waitcnt vmcnt(%0)" ::"n"(2 * NLD) : "memory");
;     else if (kt + 1 < nkt) asm volatile("s_waitcnt vmcnt(%0)" ::"n"(NLD) : "memory");
;     else asm volatile("s_waitcnt vmcnt(0)" ::: "memory");
;     asm volatile("s_waitcnt lgkmcnt(0)" ::: "memory");
;     __builtin_amdgcn_s_barrier();
;     if (kt + 3 < nkt) issue(kt + 3);
;     const bool skip = CAUSAL && (kt * 64 > q0w + 31);
;     if (!skip) {
;       const char* base = smem + (kt & 3) * STAGE;
;       f32x16 s[2];
; #pragma unroll
;       for (int sb = 0; sb < 2; ++sb) {
; #pragma unroll
;         for (int i = 0; i < 16; ++i) s[sb][i] = 0.f;
;         const char* pk = base + (sb * 32 + l31) * 256;
; #pragma unroll
;         for (int kc = 0; kc < NKC16; ++kc) {
;           const bf16x8 a = *(const bf16x8*)(pk + (((mymap * (DK / 8) + kc * 2 + h) ^ (l31 & 15)) * 16));
;           s[sb] = MFMA(a, qf[kc], s[sb]);
;         }
;         __builtin_amdgcn_sched_barrier(0);
;       }
;       const bool need_mask = CAUSAL && (kt * 64 + 63 > q0w);
;       const char* pv = base + KBYTES + l31 * 128;
;       const int vsw = (l31 >> 1) & 7;
;       bf16x8 pf[4];
;       auto expo = [&](int sb) {
; #pragma unroll
;         for (int i = 0; i < 16; ++i) {
;           float pz = __builtin_amdgcn_exp2f(s[sb][i]);
;           if (need_mask) {
;             const int key = kt * 64 + sb * 32 + crow(i, h);
;             if (key > q0w + l31) pz = 0.f;
;           }
;           s[sb][i] = pz;
;         }
; #pragma unroll
;         for (int k2 = 0; k2 < 2; ++k2) {
;           u4 pu;
;           pu.x = pack2(s[sb][k2 * 8 + 0], s[sb][k2 * 8 + 1]);
;           pu.y = pack2(s[sb][k2 * 8 + 2], s[sb][k2 * 8 + 3]);
;           pu.z = pack2(s[sb][k2 * 8 + 4], s[sb][k2 * 8 + 5]);
;           pu.w = pack2(s[sb][k2 * 8 + 6], s[sb][k2 * 8 + 7]);
;           pf[sb * 2 + k2] = __builtin_bit_cast(bf16x8, pu);
;         }
;       };
;       auto pvmm = [&](int ks) {
;         lacc = MFMA(ones, pf[ks], lacc);
; #pragma unroll
;         for (int d = 0; d < NDVB; ++d) {
;           const u4 au = *(const u4*)(pv + d * 32 * 128 + (((ks * 2 + h) ^ vsw) * 16));
;           o[d] = MFMA(__builtin_bit_cast(bf16x8, au), pf[ks], o[d]);
;         }
;       };
;       expo(0);
;       pvmm(0); pvmm(1);
;       expo(1);
.LBB0_95:
	s_waitcnt lgkmcnt(0)
	s_add_i32 s4, s65, 3
	s_cmp_ge_u32 s4, s61
	s_barrier
	s_cbranch_scc1 .LBB0_97
	s_add_i32 s4, s63, 63
	s_cmp_le_u32 s4, s100
	s_cbranch_scc0 .Lmy_d96
	s_cmp_eq_u32 s101, 1
	s_cbranch_scc0 .Lmy_d96
	s_and_b32 s4, s64, 0x18000
	v_or_b32_e32 v0, s4, v170
	v_add_u32_e32 v6, v0, v174
	v_add_u32_e32 v7, v0, v175
	v_add_u32_e32 v8, v0, v173
	v_add_u32_e32 v9, v0, v172
	ds_read_b128 v[212:215], v6
	ds_read_b128 v[216:219], v7
	ds_read_b128 v[220:223], v8
	ds_read_b128 v[224:227], v9
	ds_read_b128 v[228:231], v6 offset:8192
	ds_read_b128 v[232:235], v7 offset:8192
	ds_read_b128 v[236:239], v8 offset:8192
	ds_read_b128 v[240:243], v9 offset:8192
	v_or_b32_e32 v0, s4, v168
	v_add_u32_e32 v10, v0, v167
	v_add_u32_e32 v11, v0, v166
	v_add_u32_e32 v12, v0, v164
	v_add_u32_e32 v13, v0, v163
	s_waitcnt lgkmcnt(7)
	v_mfma_f32_32x32x16_bf16 v[112:127], v[212:215], v[140:143], 0
	s_waitcnt lgkmcnt(6)
	v_mfma_f32_32x32x16_bf16 v[112:127], v[216:219], v[136:139], v[112:127]
	s_waitcnt lgkmcnt(5)
	v_mfma_f32_32x32x16_bf16 v[112:127], v[220:223], v[132:135], v[112:127]
	s_waitcnt lgkmcnt(4)
	v_mfma_f32_32x32x16_bf16 v[112:127], v[224:227], v[128:131], v[112:127]
	ds_read_b128 v[212:215], v10 offset:16384
	ds_read_b128 v[216:219], v10 offset:20480
	s_waitcnt lgkmcnt(5)
	v_mfma_f32_32x32x16_bf16 v[96:111], v[228:231], v[140:143], 0
	ds_read_b128 v[220:223], v10 offset:24576
	ds_read_b128 v[224:227], v10 offset:28672
	s_waitcnt lgkmcnt(6)
	v_mfma_f32_32x32x16_bf16 v[96:111], v[232:235], v[136:139], v[96:111]
	s_waitcnt lgkmcnt(5)
	v_mfma_f32_32x32x16_bf16 v[96:111], v[236:239], v[132:135], v[96:111]
	s_waitcnt lgkmcnt(4)
	v_mfma_f32_32x32x16_bf16 v[96:111], v[240:243], v[128:131], v[96:111]
	ds_read_b128 v[228:231], v11 offset:16384
	ds_read_b128 v[232:235], v11 offset:20480
	ds_read_b128 v[236:239], v11 offset:24576
	ds_read_b128 v[240:243], v11 offset:28672
	v_exp_f32_e32 v112, v112
	v_exp_f32_e32 v113, v113
	v_exp_f32_e32 v114, v114
	v_exp_f32_e32 v115, v115
	v_exp_f32_e32 v116, v116
	v_exp_f32_e32 v117, v117
	v_exp_f32_e32 v118, v118
	v_exp_f32_e32 v119, v119
	v_add_f32_e32 v248, v248, v112
	v_add_f32_e32 v249, v249, v113
	v_add_f32_e32 v248, v248, v114
	v_add_f32_e32 v249, v249, v115
	v_add_f32_e32 v248, v248, v116
	v_add_f32_e32 v249, v249, v117
	v_add_f32_e32 v248, v248, v118
	v_add_f32_e32 v249, v249, v119
	v_cvt_pk_bf16_f32 v186, v112, v113
	v_cvt_pk_bf16_f32 v187, v114, v115
	v_cvt_pk_bf16_f32 v188, v116, v117
	v_cvt_pk_bf16_f32 v189, v118, v119
	s_nop 0
	v_add_u32_e32 v0, s63, v171
	v_add_u32_e32 v6, 0xc0, v0
	v_add_u32_e32 v8, 0xc4, v0
	v_ashrrev_i32_e32 v7, 31, v6
	v_ashrrev_i32_e32 v9, 31, v8
	v_lshlrev_b64 v[6:7], 11, v[6:7]
	v_lshlrev_b64 v[8:9], 11, v[8:9]
	s_add_i32 s4, s64, 0x18000
	s_and_b32 s4, s4, 0x18000
	v_lshl_add_u64 v[6:7], v[148:149], 0, v[6:7]
	v_lshl_add_u64 v[8:9], v[146:147], 0, v[8:9]
	s_add_i32 s5, s4, s35
	s_add_i32 s4, s4, s60
	s_waitcnt lgkmcnt(7)
	v_mfma_f32_32x32x16_bf16 v[64:79], v[212:215], v[186:189], v[64:79]
	ds_read_b128 v[212:215], v12 offset:16384
	v_exp_f32_e32 v120, v120
	v_exp_f32_e32 v121, v121
	v_exp_f32_e32 v122, v122
	v_exp_f32_e32 v123, v123
	v_exp_f32_e32 v124, v124
	s_waitcnt lgkmcnt(7)
	v_mfma_f32_32x32x16_bf16 v[48:63], v[216:219], v[186:189], v[48:63]
	ds_read_b128 v[216:219], v12 offset:20480
	v_exp_f32_e32 v125, v125
	v_exp_f32_e32 v126, v126
	v_exp_f32_e32 v127, v127
	v_add_f32_e32 v248, v248, v120
	v_add_f32_e32 v249, v249, v121
	s_waitcnt lgkmcnt(7)
	v_mfma_f32_32x32x16_bf16 v[32:47], v[220:223], v[186:189], v[32:47]
	ds_read_b128 v[220:223], v12 offset:24576
	v_add_f32_e32 v248, v248, v122
	v_add_f32_e32 v249, v249, v123
	v_add_f32_e32 v248, v248, v124
	v_add_f32_e32 v249, v249, v125
	v_add_f32_e32 v248, v248, v126
	s_waitcnt lgkmcnt(7)
	v_mfma_f32_32x32x16_bf16 v[16:31], v[224:227], v[186:189], v[16:31]
	ds_read_b128 v[224:227], v12 offset:28672
	v_add_f32_e32 v249, v249, v127
	v_cvt_pk_bf16_f32 v190, v120, v121
	v_cvt_pk_bf16_f32 v191, v122, v123
	v_cvt_pk_bf16_f32 v192, v124, v125
	v_cvt_pk_bf16_f32 v193, v126, v127
	s_nop 0
	s_waitcnt lgkmcnt(7)
	v_mfma_f32_32x32x16_bf16 v[64:79], v[228:231], v[190:193], v[64:79]
	ds_read_b128 v[228:231], v13 offset:16384
	v_exp_f32_e32 v96, v96
	v_exp_f32_e32 v97, v97
	v_exp_f32_e32 v98, v98
	v_exp_f32_e32 v99, v99
	v_exp_f32_e32 v100, v100
	s_waitcnt lgkmcnt(7)
	v_mfma_f32_32x32x16_bf16 v[48:63], v[232:235], v[190:193], v[48:63]
	ds_read_b128 v[232:235], v13 offset:20480
	v_exp_f32_e32 v101, v101
	v_exp_f32_e32 v102, v102
	v_exp_f32_e32 v103, v103
	v_add_f32_e32 v248, v248, v96
	v_add_f32_e32 v249, v249, v97
	s_waitcnt lgkmcnt(7)
	v_mfma_f32_32x32x16_bf16 v[32:47], v[236:239], v[190:193], v[32:47]
	ds_read_b128 v[236:239], v13 offset:24576
	v_add_f32_e32 v248, v248, v98
	v_add_f32_e32 v249, v249, v99
	v_add_f32_e32 v248, v248, v100
	v_add_f32_e32 v249, v249, v101
	v_add_f32_e32 v248, v248, v102
	s_waitcnt lgkmcnt(7)
	v_mfma_f32_32x32x16_bf16 v[16:31], v[240:243], v[190:193], v[16:31]
	ds_read_b128 v[240:243], v13 offset:28672
	v_add_f32_e32 v249, v249, v103
	v_cvt_pk_bf16_f32 v244, v96, v97
	v_cvt_pk_bf16_f32 v245, v98, v99
	v_cvt_pk_bf16_f32 v246, v100, v101
	v_cvt_pk_bf16_f32 v247, v102, v103
	s_nop 0
	s_waitcnt lgkmcnt(7)
	v_mfma_f32_32x32x16_bf16 v[64:79], v[212:215], v[244:247], v[64:79]
	v_exp_f32_e32 v104, v104
	v_exp_f32_e32 v105, v105
	v_exp_f32_e32 v106, v106
	v_exp_f32_e32 v107, v107
	v_exp_f32_e32 v108, v108
	s_waitcnt lgkmcnt(6)
	v_mfma_f32_32x32x16_bf16 v[48:63], v[216:219], v[244:247], v[48:63]
	v_exp_f32_e32 v109, v109
	v_exp_f32_e32 v110, v110
	v_exp_f32_e32 v111, v111
	v_add_f32_e32 v248, v248, v104
	v_add_f32_e32 v249, v249, v105
	s_waitcnt lgkmcnt(5)
	v_mfma_f32_32x32x16_bf16 v[32:47], v[220:223], v[244:247], v[32:47]
	v_add_f32_e32 v248, v248, v106
	v_add_f32_e32 v249, v249, v107
	v_add_f32_e32 v248, v248, v108
	v_add_f32_e32 v249, v249, v109
	v_add_f32_e32 v248, v248, v110
	s_waitcnt lgkmcnt(4)
	v_mfma_f32_32x32x16_bf16 v[16:31], v[224:227], v[244:247], v[16:31]
	v_add_f32_e32 v249, v249, v111
	v_cvt_pk_bf16_f32 v2, v104, v105
	v_cvt_pk_bf16_f32 v3, v106, v107
	v_cvt_pk_bf16_f32 v4, v108, v109
	v_cvt_pk_bf16_f32 v5, v110, v111
	s_nop 0
	s_mov_b32 m0, s5
	s_waitcnt lgkmcnt(3)
	v_mfma_f32_32x32x16_bf16 v[64:79], v[228:231], v[2:5], v[64:79]
	global_load_lds_dwordx4 v[6:7], off
	s_mov_b32 m0, s4
	s_waitcnt lgkmcnt(2)
	v_mfma_f32_32x32x16_bf16 v[48:63], v[232:235], v[2:5], v[48:63]
	global_load_lds_dwordx4 v[8:9], off
	s_add_i32 m0, s5, 0x4000
	s_waitcnt lgkmcnt(1)
	v_mfma_f32_32x32x16_bf16 v[32:47], v[236:239], v[2:5], v[32:47]
	global_load_lds_dwordx4 v[152:153], off
	s_add_i32 m0, s4, 0x4000
	s_waitcnt lgkmcnt(0)
	v_mfma_f32_32x32x16_bf16 v[16:31], v[240:243], v[2:5], v[16:31]
	global_load_lds_dwordx4 v[154:155], off
	s_branch .LBB0_99

; #define STAGE8(Q, BASE, br, kt) do { const bf16_t* sb_ = (BASE) + ((long)(br) * K + (long)(kt) * BK8); \
;     _Pragma("unroll") for (int i_ = 0; i_ < 2; ++i_) \
;       __builtin_amdgcn_global_load_lds((const unsigned*)(sb_ + goff[i_]), (unsigned*)(smem + (Q) * HTB + i_ * 8192 + wu8 * 1024), 16, 0, 0); } while (0)
; #define WAIT_V8(n) asm volatile("s_waitcnt vmcnt(" #n ")" ::: "memory")
; #define BAR8 __builtin_amdgcn_s_barrier()
; DI void gemm8p(const bf16_t* __restrict__ A, const bf16_t* __restrict__ Bt, int K, f32x4v (&acc)[2][2][4][2], char* smem) {
;     ...
; #pragma unroll
;   for (int a = 0; a < 2; ++a)
; #pragma unroll
;     for (int b = 0; b < 2; ++b)
; #pragma unroll
;       for (int m = 0; m < 4; ++m)
; #pragma unroll
;         for (int n = 0; n < 2; ++n) acc[a][b][m][n] = f32x4v{0.f, 0.f, 0.f, 0.f};
;   bf16x8 At[4][2], B0[2][2], B1[2][2];
;   const int nt = K / BK8;
;   asm volatile("s_waitcnt vmcnt(0)" ::: "memory");
;   __syncthreads();
;   STAGE8(SB8(0, 0), Bt, 0, 0); STAGE8(SA8(0, 0), A, 0, 0);
;   STAGE8(SB8(0, 1), Bt, HALF8, 0); STAGE8(SA8(0, 1), A, HALF8, 0);
;   if (wr == 1) BAR8;
;   WAIT_V8(4); BAR8;
;   STAGE8(SB8(1, 0), Bt, 0, 1); STAGE8(SA8(1, 0), A, 0, 1); STAGE8(SB8(1, 1), Bt, HALF8, 1);
;   WAIT_V8(6); BAR8;
.LBB0_463:
	s_or_b64 exec, exec, s[8:9]
	s_xor_b64 s[6:7], s[6:7], -1
	v_writelane_b32 v250, s6, 12
	v_lshl_add_u64 v[2:3], v[2:3], 0, s[92:93]
	s_waitcnt vmcnt(4)
	s_barrier
	v_writelane_b32 v250, s7, 13
	s_add_i32 s6, s10, 0x18000
	s_mov_b32 m0, s6
	s_add_i32 s7, s10, 0x1a000
	global_load_lds_dwordx4 v[2:3], off
	v_lshl_add_u64 v[2:3], v[4:5], 0, s[92:93]
	s_mov_b32 m0, s7
	s_add_i32 s8, s10, 0x8000
	global_load_lds_dwordx4 v[2:3], off
	v_lshl_add_u64 v[2:3], v[8:9], 0, s[92:93]
	s_mov_b32 m0, s8
	s_add_i32 s9, s10, 0xa000
	global_load_lds_dwordx4 v[2:3], off
	v_lshl_add_u64 v[2:3], v[6:7], 0, s[92:93]
	s_mov_b32 m0, s9
	s_add_i32 s30, s10, 0x1c000
	global_load_lds_dwordx4 v[2:3], off
	v_lshl_add_u64 v[2:3], v[10:11], 0, s[92:93]
	s_mov_b32 m0, s30
	s_add_i32 s31, s10, 0x1e000
	global_load_lds_dwordx4 v[2:3], off
	v_lshl_add_u64 v[2:3], v[12:13], 0, s[92:93]
	s_mov_b32 m0, s31
	s_xor_b64 s[4:5], s[4:5], -1
	global_load_lds_dwordx4 v[2:3], off
	v_and_b32_e32 v23, 15, v148
	v_lshlrev_b32_e32 v24, 2, v148
	v_lshlrev_b32_e32 v21, 12, v21
	s_waitcnt vmcnt(6)
	v_add3_u32 v2, v20, v18, v19
	v_mov_b32_e32 v3, v1
	v_add3_u32 v4, v16, v14, v15
	v_mov_b32_e32 v5, v1
	v_writelane_b32 v250, s4, 14
	v_and_b32_e32 v22, 48, v148
	v_lshlrev_b32_e32 v23, 6, v23
	v_and_b32_e32 v24, 32, v24
	v_and_b32_e32 v21, 0x3000, v21
	v_lshlrev_b64 v[2:3], 1, v[2:3]
	v_lshlrev_b64 v[4:5], 1, v[4:5]
	s_lshl_b64 s[52:53], s[80:81], 8
	v_writelane_b32 v250, s5, 15
	v_lshlrev_b32_e32 v17, 13, v17
	v_or_b32_e32 v21, 0x10000, v21
	v_bitop3_b32 v22, v23, v24, v22 bitop3:0x36
	s_lshr_b32 s5, s80, 6
	v_lshl_add_u64 v[132:133], s[0:1], 0, v[2:3]
	v_lshl_add_u64 v[6:7], s[52:53], 0, v[2:3]
	v_lshl_add_u64 v[8:9], s[52:53], 0, v[4:5]
	v_lshl_add_u64 v[140:141], s[2:3], 0, v[2:3]
	v_mov_b32_e32 v2, 0
	s_lshl_b32 s4, s80, 7
	s_barrier
	s_add_i32 s35, s5, -2
	v_lshl_add_u64 v[134:135], s[0:1], 0, v[4:5]
	v_lshl_add_u64 v[136:137], s[2:3], 0, v[6:7]
	v_lshl_add_u64 v[138:139], s[2:3], 0, v[8:9]
	v_lshl_add_u64 v[142:143], s[2:3], 0, v[4:5]
	v_lshl_add_u64 v[144:145], s[0:1], 0, v[8:9]
	v_lshl_add_u64 v[146:147], s[0:1], 0, v[6:7]
	s_mov_b32 s52, 0
	s_mov_b64 s[2:3], 0
	s_add_i32 s34, s10, 0xe000
	v_add_u32_e32 v150, v21, v22
	v_add_u32_e32 v149, v17, v22
	v_mov_b32_e32 v3, v2
	v_mov_b32_e32 v4, v2
	v_mov_b32_e32 v5, v2
	v_mov_b32_e32 v6, v2
	v_mov_b32_e32 v7, v2
	v_mov_b32_e32 v8, v2
	v_mov_b32_e32 v9, v2
	v_mov_b32_e32 v10, v2
	v_mov_b32_e32 v11, v2
	v_mov_b32_e32 v12, v2
	v_mov_b32_e32 v13, v2
	v_mov_b32_e32 v14, v2
	v_mov_b32_e32 v15, v2
	v_mov_b32_e32 v16, v2
	v_mov_b32_e32 v17, v2
	v_mov_b32_e32 v18, v2
	v_mov_b32_e32 v19, v2
	v_mov_b32_e32 v20, v2
	v_mov_b32_e32 v21, v2
	v_mov_b32_e32 v22, v2
	v_mov_b32_e32 v23, v2
	v_mov_b32_e32 v24, v2
	v_mov_b32_e32 v25, v2
	v_mov_b32_e32 v26, v2
	v_mov_b32_e32 v27, v2
	v_mov_b32_e32 v28, v2
	v_mov_b32_e32 v29, v2
	v_mov_b32_e32 v30, v2
	v_mov_b32_e32 v31, v2
	v_mov_b32_e32 v32, v2
	v_mov_b32_e32 v33, v2
	v_mov_b32_e32 v34, v2
	v_mov_b32_e32 v35, v2
	v_mov_b32_e32 v36, v2
	v_mov_b32_e32 v37, v2
	v_mov_b32_e32 v38, v2
	v_mov_b32_e32 v39, v2
	v_mov_b32_e32 v40, v2
	v_mov_b32_e32 v41, v2
	v_mov_b32_e32 v42, v2
	v_mov_b32_e32 v43, v2
	v_mov_b32_e32 v44, v2
	v_mov_b32_e32 v45, v2
	v_mov_b32_e32 v46, v2
	v_mov_b32_e32 v47, v2
	v_mov_b32_e32 v48, v2
	v_mov_b32_e32 v49, v2
	v_mov_b32_e32 v50, v2
	v_mov_b32_e32 v51, v2
	v_mov_b32_e32 v52, v2
	v_mov_b32_e32 v53, v2
	v_mov_b32_e32 v54, v2
	v_mov_b32_e32 v55, v2
	v_mov_b32_e32 v56, v2
	v_mov_b32_e32 v57, v2
	v_mov_b32_e32 v58, v2
	v_mov_b32_e32 v59, v2
	v_mov_b32_e32 v60, v2
	v_mov_b32_e32 v61, v2
	v_mov_b32_e32 v62, v2
	v_mov_b32_e32 v63, v2
	v_mov_b32_e32 v64, v2
	v_mov_b32_e32 v65, v2
	v_mov_b32_e32 v66, v2
	v_mov_b32_e32 v67, v2
	v_mov_b32_e32 v68, v2
	v_mov_b32_e32 v69, v2
	v_mov_b32_e32 v70, v2
	v_mov_b32_e32 v71, v2
	v_mov_b32_e32 v72, v2
	v_mov_b32_e32 v73, v2
	v_mov_b32_e32 v74, v2
	v_mov_b32_e32 v75, v2
	v_mov_b32_e32 v76, v2
	v_mov_b32_e32 v77, v2
	v_mov_b32_e32 v78, v2
	v_mov_b32_e32 v79, v2
	v_mov_b32_e32 v80, v2
	v_mov_b32_e32 v81, v2
	v_mov_b32_e32 v82, v2
	v_mov_b32_e32 v83, v2
	v_mov_b32_e32 v84, v2
	v_mov_b32_e32 v85, v2
	v_mov_b32_e32 v86, v2
	v_mov_b32_e32 v87, v2
	v_mov_b32_e32 v88, v2
	v_mov_b32_e32 v89, v2
	v_mov_b32_e32 v90, v2
	v_mov_b32_e32 v91, v2
	v_mov_b32_e32 v92, v2
	v_mov_b32_e32 v93, v2
	v_mov_b32_e32 v94, v2
	v_mov_b32_e32 v95, v2
	v_mov_b32_e32 v96, v2
	v_mov_b32_e32 v97, v2
	v_mov_b32_e32 v98, v2
	v_mov_b32_e32 v99, v2
	v_mov_b32_e32 v100, v2
	v_mov_b32_e32 v101, v2
	v_mov_b32_e32 v102, v2
	v_mov_b32_e32 v103, v2
	v_mov_b32_e32 v104, v2
	v_mov_b32_e32 v105, v2
	v_mov_b32_e32 v106, v2
	v_mov_b32_e32 v107, v2
	v_mov_b32_e32 v108, v2
	v_mov_b32_e32 v109, v2
	v_mov_b32_e32 v110, v2
	v_mov_b32_e32 v111, v2
	v_mov_b32_e32 v112, v2
	v_mov_b32_e32 v113, v2
	v_mov_b32_e32 v114, v2
	v_mov_b32_e32 v115, v2
	v_mov_b32_e32 v116, v2
	v_mov_b32_e32 v117, v2
	v_mov_b32_e32 v118, v2
	v_mov_b32_e32 v119, v2
	v_mov_b32_e32 v120, v2
	v_mov_b32_e32 v121, v2
	v_mov_b32_e32 v122, v2
	v_mov_b32_e32 v123, v2
	v_mov_b32_e32 v124, v2
	v_mov_b32_e32 v125, v2
	v_mov_b32_e32 v126, v2
	v_mov_b32_e32 v127, v2
	v_mov_b32_e32 v128, v2
	v_mov_b32_e32 v129, v2
	s_nop 0
	s_nop 0
	s_nop 0
	s_nop 0
	s_nop 0
	s_nop 0
	s_nop 0
	s_nop 0
	s_nop 0
; #define STAGE8(Q, BASE, br, kt) do { const bf16_t* sb_ = (BASE) + ((long)(br) * K + (long)(kt) * BK8); \
;     _Pragma("unroll") for (int i_ = 0; i_ < 2; ++i_) \
;       __builtin_amdgcn_global_load_lds((const unsigned*)(sb_ + goff[i_]), (unsigned*)(smem + (Q) * HTB + i_ * 8192 + wu8 * 1024), 16, 0, 0); } while (0)
; #define LDA8(dst, b, h) _Pragma("unroll") for (int m = 0; m < 4; ++m) _Pragma("unroll") for (int k = 0; k < 2; ++k) \
;     dst[m][k] = *(const bf16x8*)(la + ((b) * 2 + (h)) * HTB + (m * 2 + k) * 1024)
; #define LDB8(dst, b, h) _Pragma("unroll") for (int n = 0; n < 2; ++n) _Pragma("unroll") for (int k = 0; k < 2; ++k) \
;     dst[n][k] = *(const bf16x8*)(lb + ((b) * 2 + (h)) * HTB + (n * 2 + k) * 1024)
; #define MMA8(ai, bj, At_, Bt_) do { __builtin_amdgcn_s_setprio(1); \
;     _Pragma("unroll") for (int m = 0; m < 4; ++m) _Pragma("unroll") for (int n = 0; n < 2; ++n) _Pragma("unroll") for (int k = 0; k < 2; ++k) \
;       acc[ai][bj][m][n] = __builtin_amdgcn_mfma_f32_16x16x32_bf16(Bt_[n][k], At_[m][k], acc[ai][bj][m][n], 0, 0, 0); \
;     __builtin_amdgcn_s_setprio(0); } while (0)
; #define WAIT_V8(n) asm volatile("s_waitcnt vmcnt(" #n ")" ::: "memory")
; #define WAIT_L8(n) asm volatile("s_waitcnt lgkmcnt(" #n ")" ::: "memory")
; #define BAR8 __builtin_amdgcn_s_barrier()
; #define SCHED8 __builtin_amdgcn_sched_barrier(0)
; DI void gemm8p(const bf16_t* __restrict__ A, const bf16_t* __restrict__ Bt, int K, f32x4v (&acc)[2][2][4][2], char* smem) {
;     ...
;   for (int t = 0; t < nt - 2; t += 2) {
;     LDB8(B0, 0, 0); SCHED8; LDA8(At, 0, 0); STAGE8(SA8(1, 1), A, HALF8, t + 1);
;     WAIT_L8(8); BAR8; WAIT_L8(0); MMA8(0, 0, At, B0); BAR8; SCHED8;
;     LDB8(B1, 0, 1); STAGE8(SB8(0, 0), Bt, 0, t + 2);
;     BAR8; WAIT_L8(0); MMA8(0, 1, At, B1); BAR8;
;     LDA8(At, 0, 1); STAGE8(SA8(0, 0), A, 0, t + 2);
;     BAR8; WAIT_L8(0); MMA8(1, 0, At, B0); BAR8; SCHED8;
;     STAGE8(SB8(0, 1), Bt, HALF8, t + 2);
;     WAIT_V8(6); BAR8; MMA8(1, 1, At, B1); BAR8;
.LBB0_464:
	ds_read_b128 v[152:155], v150
	ds_read_b128 v[156:159], v150 offset:1024
	ds_read_b128 v[160:163], v150 offset:2048
	ds_read_b128 v[164:167], v150 offset:3072
	v_lshl_add_u64 v[192:193], v[144:145], 0, s[2:3]
	s_add_i32 s53, s10, 0xc000
	v_lshl_add_u64 v[220:221], v[192:193], 0, s[92:93]
	s_mov_b32 m0, s53
	v_lshl_add_u64 v[236:237], v[146:147], 0, s[2:3]
	ds_read_b128 v[168:171], v149
	ds_read_b128 v[172:175], v149 offset:1024
	ds_read_b128 v[176:179], v149 offset:2048
	ds_read_b128 v[180:183], v149 offset:3072
	ds_read_b128 v[184:187], v149 offset:4096
	ds_read_b128 v[188:191], v149 offset:5120
	ds_read_b128 v[212:215], v149 offset:6144
	ds_read_b128 v[216:219], v149 offset:7168
	global_load_lds_dwordx4 v[220:221], off
	v_lshl_add_u64 v[220:221], v[236:237], 0, s[92:93]
	s_mov_b32 m0, s34
	s_nop 0
	global_load_lds_dwordx4 v[220:221], off
	s_waitcnt lgkmcnt(8)
	s_barrier
	s_waitcnt lgkmcnt(0)
	s_setprio 1
	s_waitcnt lgkmcnt(0)
	v_mfma_f32_16x16x32_bf16 v[126:129], v[152:155], v[168:171], v[126:129]
	v_mfma_f32_16x16x32_bf16 v[122:125], v[160:163], v[168:171], v[122:125]
	v_mfma_f32_16x16x32_bf16 v[118:121], v[152:155], v[176:179], v[118:121]
	v_mfma_f32_16x16x32_bf16 v[114:117], v[160:163], v[176:179], v[114:117]
	v_mfma_f32_16x16x32_bf16 v[110:113], v[152:155], v[184:187], v[110:113]
	v_mfma_f32_16x16x32_bf16 v[106:109], v[160:163], v[184:187], v[106:109]
	v_mfma_f32_16x16x32_bf16 v[102:105], v[152:155], v[212:215], v[102:105]
	v_mfma_f32_16x16x32_bf16 v[98:101], v[160:163], v[212:215], v[98:101]
	v_mfma_f32_16x16x32_bf16 v[126:129], v[156:159], v[172:175], v[126:129]
	v_mfma_f32_16x16x32_bf16 v[122:125], v[164:167], v[172:175], v[122:125]
	v_mfma_f32_16x16x32_bf16 v[118:121], v[156:159], v[180:183], v[118:121]
	v_mfma_f32_16x16x32_bf16 v[114:117], v[164:167], v[180:183], v[114:117]
	v_mfma_f32_16x16x32_bf16 v[110:113], v[156:159], v[188:191], v[110:113]
	v_mfma_f32_16x16x32_bf16 v[106:109], v[164:167], v[188:191], v[106:109]
	v_mfma_f32_16x16x32_bf16 v[102:105], v[156:159], v[216:219], v[102:105]
	v_mfma_f32_16x16x32_bf16 v[98:101], v[164:167], v[216:219], v[98:101]
	s_setprio 0
	s_barrier
	v_lshl_add_u64 v[238:239], v[142:143], 0, s[2:3]
	s_mov_b32 m0, s11
	v_lshl_add_u64 v[240:241], v[238:239], 0, s[94:95]
	ds_read_b128 v[220:223], v150 offset:16384
	ds_read_b128 v[224:227], v150 offset:17408
	ds_read_b128 v[228:231], v150 offset:18432
	ds_read_b128 v[232:235], v150 offset:19456
	global_load_lds_dwordx4 v[240:241], off
	v_lshl_add_u64 v[240:241], v[140:141], 0, s[2:3]
	v_lshl_add_u64 v[242:243], v[240:241], 0, s[94:95]
	s_mov_b32 m0, s12
	s_add_i32 s52, s52, 2
	global_load_lds_dwordx4 v[242:243], off
	s_barrier
	s_waitcnt lgkmcnt(0)
	s_setprio 1
	s_waitcnt lgkmcnt(0)
	v_mfma_f32_16x16x32_bf16 v[94:97], v[220:223], v[168:171], v[94:97]
	v_mfma_f32_16x16x32_bf16 v[90:93], v[228:231], v[168:171], v[90:93]
	v_mfma_f32_16x16x32_bf16 v[86:89], v[220:223], v[176:179], v[86:89]
	v_mfma_f32_16x16x32_bf16 v[82:85], v[228:231], v[176:179], v[82:85]
	v_mfma_f32_16x16x32_bf16 v[78:81], v[220:223], v[184:187], v[78:81]
	v_mfma_f32_16x16x32_bf16 v[74:77], v[228:231], v[184:187], v[74:77]
	v_mfma_f32_16x16x32_bf16 v[70:73], v[220:223], v[212:215], v[70:73]
	v_mfma_f32_16x16x32_bf16 v[66:69], v[228:231], v[212:215], v[66:69]
	v_mfma_f32_16x16x32_bf16 v[94:97], v[224:227], v[172:175], v[94:97]
	v_mfma_f32_16x16x32_bf16 v[90:93], v[232:235], v[172:175], v[90:93]
	v_mfma_f32_16x16x32_bf16 v[86:89], v[224:227], v[180:183], v[86:89]
	v_mfma_f32_16x16x32_bf16 v[82:85], v[232:235], v[180:183], v[82:85]
	v_mfma_f32_16x16x32_bf16 v[78:81], v[224:227], v[188:191], v[78:81]
	v_mfma_f32_16x16x32_bf16 v[74:77], v[232:235], v[188:191], v[74:77]
	v_mfma_f32_16x16x32_bf16 v[70:73], v[224:227], v[216:219], v[70:73]
	v_mfma_f32_16x16x32_bf16 v[66:69], v[232:235], v[216:219], v[66:69]
	s_setprio 0
	v_lshl_add_u64 v[242:243], v[134:135], 0, s[2:3]
	s_mov_b32 m0, s10
	v_lshl_add_u64 v[244:245], v[242:243], 0, s[94:95]
	s_barrier
	ds_read_b128 v[168:171], v149 offset:16384
	ds_read_b128 v[172:175], v149 offset:17408
	ds_read_b128 v[176:179], v149 offset:18432
	ds_read_b128 v[180:183], v149 offset:19456
	ds_read_b128 v[184:187], v149 offset:20480
	ds_read_b128 v[188:191], v149 offset:21504
	ds_read_b128 v[212:215], v149 offset:22528
	ds_read_b128 v[216:219], v149 offset:23552
	global_load_lds_dwordx4 v[244:245], off
	v_lshl_add_u64 v[244:245], v[132:133], 0, s[2:3]
	v_lshl_add_u64 v[246:247], v[244:245], 0, s[94:95]
	s_mov_b32 m0, s13
	s_nop 0
	global_load_lds_dwordx4 v[246:247], off
	s_barrier
	s_waitcnt lgkmcnt(0)
	s_setprio 1
	s_waitcnt lgkmcnt(0)
	v_mfma_f32_16x16x32_bf16 v[62:65], v[152:155], v[168:171], v[62:65]
	v_mfma_f32_16x16x32_bf16 v[58:61], v[160:163], v[168:171], v[58:61]
	v_mfma_f32_16x16x32_bf16 v[54:57], v[152:155], v[176:179], v[54:57]
	v_mfma_f32_16x16x32_bf16 v[50:53], v[160:163], v[176:179], v[50:53]
	v_mfma_f32_16x16x32_bf16 v[46:49], v[152:155], v[184:187], v[46:49]
	v_mfma_f32_16x16x32_bf16 v[42:45], v[160:163], v[184:187], v[42:45]
	v_mfma_f32_16x16x32_bf16 v[38:41], v[152:155], v[212:215], v[38:41]
	v_mfma_f32_16x16x32_bf16 v[34:37], v[160:163], v[212:215], v[34:37]
	v_mfma_f32_16x16x32_bf16 v[62:65], v[156:159], v[172:175], v[62:65]
	v_mfma_f32_16x16x32_bf16 v[58:61], v[164:167], v[172:175], v[58:61]
	v_mfma_f32_16x16x32_bf16 v[54:57], v[156:159], v[180:183], v[54:57]
	v_mfma_f32_16x16x32_bf16 v[50:53], v[164:167], v[180:183], v[50:53]
	v_mfma_f32_16x16x32_bf16 v[46:49], v[156:159], v[188:191], v[46:49]
	v_mfma_f32_16x16x32_bf16 v[42:45], v[164:167], v[188:191], v[42:45]
	v_mfma_f32_16x16x32_bf16 v[38:41], v[156:159], v[216:219], v[38:41]
	v_mfma_f32_16x16x32_bf16 v[34:37], v[164:167], v[216:219], v[34:37]
	s_setprio 0
	s_barrier
; #define STAGE8(Q, BASE, br, kt) do { const bf16_t* sb_ = (BASE) + ((long)(br) * K + (long)(kt) * BK8); \
;     _Pragma("unroll") for (int i_ = 0; i_ < 2; ++i_) \
;       __builtin_amdgcn_global_load_lds((const unsigned*)(sb_ + goff[i_]), (unsigned*)(smem + (Q) * HTB + i_ * 8192 + wu8 * 1024), 16, 0, 0); } while (0)
; #define LDA8(dst, b, h) _Pragma("unroll") for (int m = 0; m < 4; ++m) _Pragma("unroll") for (int k = 0; k < 2; ++k) \
;     dst[m][k] = *(const bf16x8*)(la + ((b) * 2 + (h)) * HTB + (m * 2 + k) * 1024)
; #define LDB8(dst, b, h) _Pragma("unroll") for (int n = 0; n < 2; ++n) _Pragma("unroll") for (int k = 0; k < 2; ++k) \
;     dst[n][k] = *(const bf16x8*)(lb + ((b) * 2 + (h)) * HTB + (n * 2 + k) * 1024)
; #define MMA8(ai, bj, At_, Bt_) do { __builtin_amdgcn_s_setprio(1); \
;     _Pragma("unroll") for (int m = 0; m < 4; ++m) _Pragma("unroll") for (int n = 0; n < 2; ++n) _Pragma("unroll") for (int k = 0; k < 2; ++k) \
;       acc[ai][bj][m][n] = __builtin_amdgcn_mfma_f32_16x16x32_bf16(Bt_[n][k], At_[m][k], acc[ai][bj][m][n], 0, 0, 0); \
;     __builtin_amdgcn_s_setprio(0); } while (0)
; #define WAIT_V8(n) asm volatile("s_waitcnt vmcnt(" #n ")" ::: "memory")
; #define WAIT_L8(n) asm volatile("s_waitcnt lgkmcnt(" #n ")" ::: "memory")
; #define BAR8 __builtin_amdgcn_s_barrier()
; #define SCHED8 __builtin_amdgcn_sched_barrier(0)
; DI void gemm8p(const bf16_t* __restrict__ A, const bf16_t* __restrict__ Bt, int K, f32x4v (&acc)[2][2][4][2], char* smem) {
;     ...
;     STAGE8(SB8(0, 1), Bt, HALF8, t + 2);
;     WAIT_V8(6); BAR8; MMA8(1, 1, At, B1); BAR8;
;     LDB8(B0, 1, 0); SCHED8; LDA8(At, 1, 0); STAGE8(SA8(0, 1), A, HALF8, t + 2);
;     WAIT_L8(8); BAR8; WAIT_L8(0); MMA8(0, 0, At, B0); BAR8; SCHED8;
;     LDB8(B1, 1, 1); STAGE8(SB8(1, 0), Bt, 0, t + 3);
;     BAR8; WAIT_L8(0); MMA8(0, 1, At, B1); BAR8;
;     LDA8(At, 1, 1); STAGE8(SA8(1, 0), A, 0, t + 3);
;     BAR8; WAIT_L8(0); MMA8(1, 0, At, B0); BAR8; SCHED8;
	v_lshl_add_u64 v[246:247], v[138:139], 0, s[2:3]
	s_mov_b32 m0, s16
	v_lshl_add_u64 v[152:153], v[246:247], 0, s[94:95]
	v_lshl_add_u64 v[248:249], v[136:137], 0, s[2:3]
	global_load_lds_dwordx4 v[152:153], off
	v_lshl_add_u64 v[152:153], v[248:249], 0, s[94:95]
	s_mov_b32 m0, s17
	s_nop 0
	global_load_lds_dwordx4 v[152:153], off
	s_waitcnt vmcnt(6)
	s_barrier
	s_setprio 1
	v_mfma_f32_16x16x32_bf16 v[30:33], v[220:223], v[168:171], v[30:33]
	v_mfma_f32_16x16x32_bf16 v[26:29], v[228:231], v[168:171], v[26:29]
	v_mfma_f32_16x16x32_bf16 v[22:25], v[220:223], v[176:179], v[22:25]
	v_mfma_f32_16x16x32_bf16 v[18:21], v[228:231], v[176:179], v[18:21]
	v_mfma_f32_16x16x32_bf16 v[14:17], v[220:223], v[184:187], v[14:17]
	v_mfma_f32_16x16x32_bf16 v[10:13], v[228:231], v[184:187], v[10:13]
	v_mfma_f32_16x16x32_bf16 v[6:9], v[220:223], v[212:215], v[6:9]
	v_mfma_f32_16x16x32_bf16 v[2:5], v[228:231], v[212:215], v[2:5]
	v_mfma_f32_16x16x32_bf16 v[30:33], v[224:227], v[172:175], v[30:33]
	v_mfma_f32_16x16x32_bf16 v[26:29], v[232:235], v[172:175], v[26:29]
	v_mfma_f32_16x16x32_bf16 v[22:25], v[224:227], v[180:183], v[22:25]
	v_mfma_f32_16x16x32_bf16 v[18:21], v[232:235], v[180:183], v[18:21]
	v_mfma_f32_16x16x32_bf16 v[14:17], v[224:227], v[188:191], v[14:17]
	v_mfma_f32_16x16x32_bf16 v[10:13], v[232:235], v[188:191], v[10:13]
	v_mfma_f32_16x16x32_bf16 v[6:9], v[224:227], v[216:219], v[6:9]
	v_mfma_f32_16x16x32_bf16 v[2:5], v[232:235], v[216:219], v[2:5]
	s_setprio 0
	s_barrier
	ds_read_b128 v[152:155], v150 offset:32768
	ds_read_b128 v[156:159], v150 offset:33792
	ds_read_b128 v[160:163], v150 offset:34816
	ds_read_b128 v[164:167], v150 offset:35840
	s_mov_b32 m0, s18
	v_lshl_add_u64 v[192:193], v[192:193], 0, s[94:95]
	ds_read_b128 v[168:171], v149 offset:32768
	ds_read_b128 v[172:175], v149 offset:33792
	ds_read_b128 v[176:179], v149 offset:34816
	ds_read_b128 v[180:183], v149 offset:35840
	ds_read_b128 v[184:187], v149 offset:36864
	ds_read_b128 v[188:191], v149 offset:37888
	ds_read_b128 v[212:215], v149 offset:38912
	ds_read_b128 v[216:219], v149 offset:39936
	global_load_lds_dwordx4 v[192:193], off
	v_lshl_add_u64 v[192:193], v[236:237], 0, s[94:95]
	s_mov_b32 m0, s19
	s_nop 0
	global_load_lds_dwordx4 v[192:193], off
	s_waitcnt lgkmcnt(8)
	s_barrier
	s_waitcnt lgkmcnt(0)
	s_setprio 1
	s_waitcnt lgkmcnt(0)
	v_mfma_f32_16x16x32_bf16 v[126:129], v[152:155], v[168:171], v[126:129]
	v_mfma_f32_16x16x32_bf16 v[122:125], v[160:163], v[168:171], v[122:125]
	v_mfma_f32_16x16x32_bf16 v[118:121], v[152:155], v[176:179], v[118:121]
	v_mfma_f32_16x16x32_bf16 v[114:117], v[160:163], v[176:179], v[114:117]
	v_mfma_f32_16x16x32_bf16 v[110:113], v[152:155], v[184:187], v[110:113]
	v_mfma_f32_16x16x32_bf16 v[106:109], v[160:163], v[184:187], v[106:109]
	v_mfma_f32_16x16x32_bf16 v[102:105], v[152:155], v[212:215], v[102:105]
	v_mfma_f32_16x16x32_bf16 v[98:101], v[160:163], v[212:215], v[98:101]
	v_mfma_f32_16x16x32_bf16 v[126:129], v[156:159], v[172:175], v[126:129]
	v_mfma_f32_16x16x32_bf16 v[122:125], v[164:167], v[172:175], v[122:125]
	v_mfma_f32_16x16x32_bf16 v[118:121], v[156:159], v[180:183], v[118:121]
	v_mfma_f32_16x16x32_bf16 v[114:117], v[164:167], v[180:183], v[114:117]
	v_mfma_f32_16x16x32_bf16 v[110:113], v[156:159], v[188:191], v[110:113]
	v_mfma_f32_16x16x32_bf16 v[106:109], v[164:167], v[188:191], v[106:109]
	v_mfma_f32_16x16x32_bf16 v[102:105], v[156:159], v[216:219], v[102:105]
	v_mfma_f32_16x16x32_bf16 v[98:101], v[164:167], v[216:219], v[98:101]
	s_setprio 0
	s_barrier
	s_mov_b32 m0, s6
	v_lshl_add_u64 v[192:193], v[238:239], 0, s[28:29]
	ds_read_b128 v[220:223], v150 offset:49152
	ds_read_b128 v[224:227], v150 offset:50176
	ds_read_b128 v[228:231], v150 offset:51200
	ds_read_b128 v[232:235], v150 offset:52224
	global_load_lds_dwordx4 v[192:193], off
	v_lshl_add_u64 v[192:193], v[240:241], 0, s[28:29]
	s_mov_b32 m0, s7
	s_nop 0
	global_load_lds_dwordx4 v[192:193], off
	s_barrier
	s_waitcnt lgkmcnt(0)
	s_setprio 1
	s_waitcnt lgkmcnt(0)
	v_mfma_f32_16x16x32_bf16 v[94:97], v[220:223], v[168:171], v[94:97]
	v_mfma_f32_16x16x32_bf16 v[90:93], v[228:231], v[168:171], v[90:93]
	v_mfma_f32_16x16x32_bf16 v[86:89], v[220:223], v[176:179], v[86:89]
	v_mfma_f32_16x16x32_bf16 v[82:85], v[228:231], v[176:179], v[82:85]
	v_mfma_f32_16x16x32_bf16 v[78:81], v[220:223], v[184:187], v[78:81]
	v_mfma_f32_16x16x32_bf16 v[74:77], v[228:231], v[184:187], v[74:77]
	v_mfma_f32_16x16x32_bf16 v[70:73], v[220:223], v[212:215], v[70:73]
	v_mfma_f32_16x16x32_bf16 v[66:69], v[228:231], v[212:215], v[66:69]
	v_mfma_f32_16x16x32_bf16 v[94:97], v[224:227], v[172:175], v[94:97]
	v_mfma_f32_16x16x32_bf16 v[90:93], v[232:235], v[172:175], v[90:93]
	v_mfma_f32_16x16x32_bf16 v[86:89], v[224:227], v[180:183], v[86:89]
	v_mfma_f32_16x16x32_bf16 v[82:85], v[232:235], v[180:183], v[82:85]
	v_mfma_f32_16x16x32_bf16 v[78:81], v[224:227], v[188:191], v[78:81]
	v_mfma_f32_16x16x32_bf16 v[74:77], v[232:235], v[188:191], v[74:77]
	v_mfma_f32_16x16x32_bf16 v[70:73], v[224:227], v[216:219], v[70:73]
	v_mfma_f32_16x16x32_bf16 v[66:69], v[232:235], v[216:219], v[66:69]
	s_setprio 0
	s_mov_b32 m0, s8
	v_lshl_add_u64 v[192:193], v[242:243], 0, s[28:29]
	s_barrier
	ds_read_b128 v[168:171], v149 offset:49152
	ds_read_b128 v[172:175], v149 offset:50176
	ds_read_b128 v[176:179], v149 offset:51200
	ds_read_b128 v[180:183], v149 offset:52224
	ds_read_b128 v[184:187], v149 offset:53248
	ds_read_b128 v[188:191], v149 offset:54272
	ds_read_b128 v[212:215], v149 offset:55296
	ds_read_b128 v[216:219], v149 offset:56320
	global_load_lds_dwordx4 v[192:193], off
	v_lshl_add_u64 v[192:193], v[244:245], 0, s[28:29]
	s_mov_b32 m0, s9
	s_nop 0
	global_load_lds_dwordx4 v[192:193], off
	s_barrier
; #define STAGE8(Q, BASE, br, kt) do { const bf16_t* sb_ = (BASE) + ((long)(br) * K + (long)(kt) * BK8); \
;     _Pragma("unroll") for (int i_ = 0; i_ < 2; ++i_) \
;       __builtin_amdgcn_global_load_lds((const unsigned*)(sb_ + goff[i_]), (unsigned*)(smem + (Q) * HTB + i_ * 8192 + wu8 * 1024), 16, 0, 0); } while (0)
; #define LDA8(dst, b, h) _Pragma("unroll") for (int m = 0; m < 4; ++m) _Pragma("unroll") for (int k = 0; k < 2; ++k) \
;     dst[m][k] = *(const bf16x8*)(la + ((b) * 2 + (h)) * HTB + (m * 2 + k) * 1024)
; #define LDB8(dst, b, h) _Pragma("unroll") for (int n = 0; n < 2; ++n) _Pragma("unroll") for (int k = 0; k < 2; ++k) \
;     dst[n][k] = *(const bf16x8*)(lb + ((b) * 2 + (h)) * HTB + (n * 2 + k) * 1024)
; #define MMA8(ai, bj, At_, Bt_) do { __builtin_amdgcn_s_setprio(1); \
;     _Pragma("unroll") for (int m = 0; m < 4; ++m) _Pragma("unroll") for (int n = 0; n < 2; ++n) _Pragma("unroll") for (int k = 0; k < 2; ++k) \
;       acc[ai][bj][m][n] = __builtin_amdgcn_mfma_f32_16x16x32_bf16(Bt_[n][k], At_[m][k], acc[ai][bj][m][n], 0, 0, 0); \
;     __builtin_amdgcn_s_setprio(0); } while (0)
; #define WAIT_V8(n) asm volatile("s_waitcnt vmcnt(" #n ")" ::: "memory")
; #define WAIT_L8(n) asm volatile("s_waitcnt lgkmcnt(" #n ")" ::: "memory")
; #define BAR8 __builtin_amdgcn_s_barrier()
; #define SCHED8 __builtin_amdgcn_sched_barrier(0)
; DI void gemm8p(const bf16_t* __restrict__ A, const bf16_t* __restrict__ Bt, int K, f32x4v (&acc)[2][2][4][2], char* smem) {
;     ...
;     LDA8(At, 1, 1); STAGE8(SA8(1, 0), A, 0, t + 3);
;     BAR8; WAIT_L8(0); MMA8(1, 0, At, B0); BAR8; SCHED8;
;     STAGE8(SB8(1, 1), Bt, HALF8, t + 3);
;     WAIT_V8(6); BAR8; MMA8(1, 1, At, B1); BAR8;
;   }
;   { LDB8(B0, 0, 0); LDA8(At, 0, 0); STAGE8(SA8(1, 1), A, HALF8, nt - 1);
;     BAR8; WAIT_L8(0); MMA8(0, 0, At, B0); BAR8;
;     LDB8(B1, 0, 1); BAR8; WAIT_L8(0); MMA8(0, 1, At, B1); BAR8;
;     LDA8(At, 0, 1); WAIT_V8(4); BAR8; WAIT_L8(0); MMA8(1, 0, At, B0); MMA8(1, 1, At, B1); BAR8; }
;   { LDB8(B0, 1, 0); LDA8(At, 1, 0); WAIT_V8(2); BAR8; WAIT_L8(0); MMA8(0, 0, At, B0); BAR8;
	s_waitcnt lgkmcnt(0)
	s_setprio 1
	s_waitcnt lgkmcnt(0)
	v_mfma_f32_16x16x32_bf16 v[62:65], v[152:155], v[168:171], v[62:65]
	v_mfma_f32_16x16x32_bf16 v[58:61], v[160:163], v[168:171], v[58:61]
	v_mfma_f32_16x16x32_bf16 v[54:57], v[152:155], v[176:179], v[54:57]
	v_mfma_f32_16x16x32_bf16 v[50:53], v[160:163], v[176:179], v[50:53]
	v_mfma_f32_16x16x32_bf16 v[46:49], v[152:155], v[184:187], v[46:49]
	v_mfma_f32_16x16x32_bf16 v[42:45], v[160:163], v[184:187], v[42:45]
	v_mfma_f32_16x16x32_bf16 v[38:41], v[152:155], v[212:215], v[38:41]
	v_mfma_f32_16x16x32_bf16 v[34:37], v[160:163], v[212:215], v[34:37]
	v_mfma_f32_16x16x32_bf16 v[62:65], v[156:159], v[172:175], v[62:65]
	v_mfma_f32_16x16x32_bf16 v[58:61], v[164:167], v[172:175], v[58:61]
	v_mfma_f32_16x16x32_bf16 v[54:57], v[156:159], v[180:183], v[54:57]
	v_mfma_f32_16x16x32_bf16 v[50:53], v[164:167], v[180:183], v[50:53]
	v_mfma_f32_16x16x32_bf16 v[46:49], v[156:159], v[188:191], v[46:49]
	v_mfma_f32_16x16x32_bf16 v[42:45], v[164:167], v[188:191], v[42:45]
	v_mfma_f32_16x16x32_bf16 v[38:41], v[156:159], v[216:219], v[38:41]
	v_mfma_f32_16x16x32_bf16 v[34:37], v[164:167], v[216:219], v[34:37]
	s_setprio 0
	s_barrier
	s_mov_b32 m0, s30
	v_lshl_add_u64 v[152:153], v[246:247], 0, s[28:29]
	global_load_lds_dwordx4 v[152:153], off
	v_lshl_add_u64 v[152:153], v[248:249], 0, s[28:29]
	s_mov_b32 m0, s31
	s_nop 0
	global_load_lds_dwordx4 v[152:153], off
	s_waitcnt vmcnt(6)
	s_barrier
	s_setprio 1
	v_mfma_f32_16x16x32_bf16 v[30:33], v[220:223], v[168:171], v[30:33]
	v_mfma_f32_16x16x32_bf16 v[26:29], v[228:231], v[168:171], v[26:29]
	v_mfma_f32_16x16x32_bf16 v[22:25], v[220:223], v[176:179], v[22:25]
	v_mfma_f32_16x16x32_bf16 v[18:21], v[228:231], v[176:179], v[18:21]
	v_mfma_f32_16x16x32_bf16 v[14:17], v[220:223], v[184:187], v[14:17]
	v_mfma_f32_16x16x32_bf16 v[10:13], v[228:231], v[184:187], v[10:13]
	v_mfma_f32_16x16x32_bf16 v[6:9], v[220:223], v[212:215], v[6:9]
	v_mfma_f32_16x16x32_bf16 v[2:5], v[228:231], v[212:215], v[2:5]
	v_mfma_f32_16x16x32_bf16 v[30:33], v[224:227], v[172:175], v[30:33]
	v_mfma_f32_16x16x32_bf16 v[26:29], v[232:235], v[172:175], v[26:29]
	v_mfma_f32_16x16x32_bf16 v[22:25], v[224:227], v[180:183], v[22:25]
	v_mfma_f32_16x16x32_bf16 v[18:21], v[232:235], v[180:183], v[18:21]
	v_mfma_f32_16x16x32_bf16 v[14:17], v[224:227], v[188:191], v[14:17]
	v_mfma_f32_16x16x32_bf16 v[10:13], v[232:235], v[188:191], v[10:13]
	v_mfma_f32_16x16x32_bf16 v[6:9], v[224:227], v[216:219], v[6:9]
	v_mfma_f32_16x16x32_bf16 v[2:5], v[232:235], v[216:219], v[2:5]
	s_setprio 0
	s_add_u32 s2, s2, 0x100
	s_addc_u32 s3, s3, 0
	s_cmp_lt_u32 s52, s35
	s_barrier
	s_cbranch_scc1 .LBB0_464
	s_add_i32 s80, s5, -1
	s_lshl_b64 s[2:3], s[80:81], 7
	s_add_u32 s0, s0, s2
	s_addc_u32 s1, s1, s3
	s_lshl_b32 s2, s4, 1
	s_add_u32 s0, s0, s2
	s_addc_u32 s1, s1, 0
	s_mov_b32 m0, s53
	v_lshl_add_u64 v[184:185], v[0:1], 1, s[0:1]
	ds_read_b128 v[132:135], v150
	ds_read_b128 v[136:139], v150 offset:1024
	ds_read_b128 v[140:143], v150 offset:2048
	ds_read_b128 v[144:147], v150 offset:3072
	ds_read_b128 v[152:155], v149
	ds_read_b128 v[156:159], v149 offset:1024
	ds_read_b128 v[160:163], v149 offset:2048
	ds_read_b128 v[164:167], v149 offset:3072
	ds_read_b128 v[168:171], v149 offset:4096
	ds_read_b128 v[172:175], v149 offset:5120
	ds_read_b128 v[176:179], v149 offset:6144
	ds_read_b128 v[180:183], v149 offset:7168
	global_load_lds_dwordx4 v[184:185], off
	v_lshl_add_u64 v[130:131], v[130:131], 1, s[0:1]
	s_mov_b32 m0, s34
	s_nop 0
	global_load_lds_dwordx4 v[130:131], off
	s_barrier
	s_waitcnt lgkmcnt(0)
	s_setprio 1
	s_waitcnt lgkmcnt(0)
	v_mfma_f32_16x16x32_bf16 v[126:129], v[132:135], v[152:155], v[126:129]
	v_mfma_f32_16x16x32_bf16 v[122:125], v[140:143], v[152:155], v[122:125]
	v_mfma_f32_16x16x32_bf16 v[118:121], v[132:135], v[160:163], v[118:121]
	v_mfma_f32_16x16x32_bf16 v[114:117], v[140:143], v[160:163], v[114:117]
	v_mfma_f32_16x16x32_bf16 v[102:105], v[132:135], v[176:179], v[102:105]
	v_mfma_f32_16x16x32_bf16 v[98:101], v[140:143], v[176:179], v[98:101]
	v_mfma_f32_16x16x32_bf16 v[126:129], v[136:139], v[156:159], v[126:129]
	v_mfma_f32_16x16x32_bf16 v[122:125], v[144:147], v[156:159], v[122:125]
	v_mfma_f32_16x16x32_bf16 v[118:121], v[136:139], v[164:167], v[118:121]
	v_mfma_f32_16x16x32_bf16 v[114:117], v[144:147], v[164:167], v[114:117]
	v_mfma_f32_16x16x32_bf16 v[110:113], v[132:135], v[168:171], v[110:113]
	v_mfma_f32_16x16x32_bf16 v[106:109], v[140:143], v[168:171], v[106:109]
	v_mfma_f32_16x16x32_bf16 v[102:105], v[136:139], v[180:183], v[102:105]
	v_mfma_f32_16x16x32_bf16 v[98:101], v[144:147], v[180:183], v[98:101]
	v_mfma_f32_16x16x32_bf16 v[184:187], v[136:139], v[172:175], v[110:113]
	v_mfma_f32_16x16x32_bf16 v[188:191], v[144:147], v[172:175], v[106:109]
	s_setprio 0
	s_barrier
	s_nop 1
	ds_read_b128 v[106:109], v150 offset:16384
	ds_read_b128 v[110:113], v150 offset:17408
	ds_read_b128 v[212:215], v150 offset:18432
	ds_read_b128 v[216:219], v150 offset:19456
	s_barrier
	s_waitcnt lgkmcnt(0)
	s_setprio 1
	s_waitcnt lgkmcnt(0)
	v_mfma_f32_16x16x32_bf16 v[86:89], v[106:109], v[160:163], v[86:89]
	v_mfma_f32_16x16x32_bf16 v[82:85], v[212:215], v[160:163], v[82:85]
	v_mfma_f32_16x16x32_bf16 v[70:73], v[106:109], v[176:179], v[70:73]
	v_mfma_f32_16x16x32_bf16 v[66:69], v[212:215], v[176:179], v[66:69]
	v_mfma_f32_16x16x32_bf16 v[94:97], v[106:109], v[152:155], v[94:97]
	v_mfma_f32_16x16x32_bf16 v[90:93], v[212:215], v[152:155], v[90:93]
	v_mfma_f32_16x16x32_bf16 v[86:89], v[110:113], v[164:167], v[86:89]
	v_mfma_f32_16x16x32_bf16 v[82:85], v[216:219], v[164:167], v[82:85]
	v_mfma_f32_16x16x32_bf16 v[78:81], v[106:109], v[168:171], v[78:81]
	v_mfma_f32_16x16x32_bf16 v[74:77], v[212:215], v[168:171], v[74:77]
	v_mfma_f32_16x16x32_bf16 v[70:73], v[110:113], v[180:183], v[70:73]
	v_mfma_f32_16x16x32_bf16 v[66:69], v[216:219], v[180:183], v[66:69]
	v_mfma_f32_16x16x32_bf16 v[220:223], v[110:113], v[156:159], v[94:97]
	v_mfma_f32_16x16x32_bf16 v[152:155], v[216:219], v[156:159], v[90:93]
	v_mfma_f32_16x16x32_bf16 v[156:159], v[110:113], v[172:175], v[78:81]
	v_mfma_f32_16x16x32_bf16 v[160:163], v[216:219], v[172:175], v[74:77]
	s_setprio 0
	s_barrier
; #define LDA8(dst, b, h) _Pragma("unroll") for (int m = 0; m < 4; ++m) _Pragma("unroll") for (int k = 0; k < 2; ++k) \
;     dst[m][k] = *(const bf16x8*)(la + ((b) * 2 + (h)) * HTB + (m * 2 + k) * 1024)
; #define LDB8(dst, b, h) _Pragma("unroll") for (int n = 0; n < 2; ++n) _Pragma("unroll") for (int k = 0; k < 2; ++k) \
;     dst[n][k] = *(const bf16x8*)(lb + ((b) * 2 + (h)) * HTB + (n * 2 + k) * 1024)
; #define MMA8(ai, bj, At_, Bt_) do { __builtin_amdgcn_s_setprio(1); \
;     _Pragma("unroll") for (int m = 0; m < 4; ++m) _Pragma("unroll") for (int n = 0; n < 2; ++n) _Pragma("unroll") for (int k = 0; k < 2; ++k) \
;       acc[ai][bj][m][n] = __builtin_amdgcn_mfma_f32_16x16x32_bf16(Bt_[n][k], At_[m][k], acc[ai][bj][m][n], 0, 0, 0); \
;     __builtin_amdgcn_s_setprio(0); } while (0)
; #define WAIT_V8(n) asm volatile("s_waitcnt vmcnt(" #n ")" ::: "memory")
; #define WAIT_L8(n) asm volatile("s_waitcnt lgkmcnt(" #n ")" ::: "memory")
; #define BAR8 __builtin_amdgcn_s_barrier()
; DI void gemm8p(const bf16_t* __restrict__ A, const bf16_t* __restrict__ Bt, int K, f32x4v (&acc)[2][2][4][2], char* smem) {
;     ...
;     LDB8(B1, 0, 1); BAR8; WAIT_L8(0); MMA8(0, 1, At, B1); BAR8;
;     LDA8(At, 0, 1); WAIT_V8(4); BAR8; WAIT_L8(0); MMA8(1, 0, At, B0); MMA8(1, 1, At, B1); BAR8; }
;   { LDB8(B0, 1, 0); LDA8(At, 1, 0); WAIT_V8(2); BAR8; WAIT_L8(0); MMA8(0, 0, At, B0); BAR8;
;     LDB8(B1, 1, 1); WAIT_V8(0); BAR8; WAIT_L8(0); MMA8(0, 1, At, B1); BAR8;
;     LDA8(At, 1, 1); BAR8; WAIT_L8(0); MMA8(1, 0, At, B0); MMA8(1, 1, At, B1); BAR8; }
	s_nop 0
	ds_read_b128 v[74:77], v149 offset:16384
	ds_read_b128 v[78:81], v149 offset:17408
	ds_read_b128 v[90:93], v149 offset:18432
	ds_read_b128 v[94:97], v149 offset:19456
	ds_read_b128 v[164:167], v149 offset:20480
	ds_read_b128 v[168:171], v149 offset:21504
	ds_read_b128 v[172:175], v149 offset:22528
	ds_read_b128 v[176:179], v149 offset:23552
	s_waitcnt vmcnt(4)
	s_barrier
	s_waitcnt lgkmcnt(0)
	s_setprio 1
	s_waitcnt lgkmcnt(0)
	v_mfma_f32_16x16x32_bf16 v[62:65], v[132:135], v[74:77], v[62:65]
	v_mfma_f32_16x16x32_bf16 v[58:61], v[140:143], v[74:77], v[58:61]
	v_mfma_f32_16x16x32_bf16 v[54:57], v[132:135], v[90:93], v[54:57]
	v_mfma_f32_16x16x32_bf16 v[50:53], v[140:143], v[90:93], v[50:53]
	v_mfma_f32_16x16x32_bf16 v[38:41], v[132:135], v[172:175], v[38:41]
	v_mfma_f32_16x16x32_bf16 v[34:37], v[140:143], v[172:175], v[34:37]
	v_mfma_f32_16x16x32_bf16 v[62:65], v[136:139], v[78:81], v[62:65]
	v_mfma_f32_16x16x32_bf16 v[58:61], v[144:147], v[78:81], v[58:61]
	v_mfma_f32_16x16x32_bf16 v[54:57], v[136:139], v[94:97], v[54:57]
	v_mfma_f32_16x16x32_bf16 v[50:53], v[144:147], v[94:97], v[50:53]
	v_mfma_f32_16x16x32_bf16 v[46:49], v[132:135], v[164:167], v[46:49]
	v_mfma_f32_16x16x32_bf16 v[42:45], v[140:143], v[164:167], v[42:45]
	v_mfma_f32_16x16x32_bf16 v[38:41], v[136:139], v[176:179], v[38:41]
	v_mfma_f32_16x16x32_bf16 v[34:37], v[144:147], v[176:179], v[34:37]
	v_mfma_f32_16x16x32_bf16 v[180:183], v[136:139], v[168:171], v[46:49]
	v_mfma_f32_16x16x32_bf16 v[224:227], v[144:147], v[168:171], v[42:45]
	s_setprio 0
	s_setprio 1
	v_mfma_f32_16x16x32_bf16 v[22:25], v[106:109], v[90:93], v[22:25]
	v_mfma_f32_16x16x32_bf16 v[18:21], v[212:215], v[90:93], v[18:21]
	v_mfma_f32_16x16x32_bf16 v[6:9], v[106:109], v[172:175], v[6:9]
	v_mfma_f32_16x16x32_bf16 v[2:5], v[212:215], v[172:175], v[2:5]
	v_mfma_f32_16x16x32_bf16 v[30:33], v[106:109], v[74:77], v[30:33]
	v_mfma_f32_16x16x32_bf16 v[26:29], v[212:215], v[74:77], v[26:29]
	v_mfma_f32_16x16x32_bf16 v[22:25], v[110:113], v[94:97], v[22:25]
	v_mfma_f32_16x16x32_bf16 v[18:21], v[216:219], v[94:97], v[18:21]
	v_mfma_f32_16x16x32_bf16 v[14:17], v[106:109], v[164:167], v[14:17]
	v_mfma_f32_16x16x32_bf16 v[10:13], v[212:215], v[164:167], v[10:13]
	v_mfma_f32_16x16x32_bf16 v[6:9], v[110:113], v[176:179], v[6:9]
	v_mfma_f32_16x16x32_bf16 v[2:5], v[216:219], v[176:179], v[2:5]
	v_mfma_f32_16x16x32_bf16 v[130:133], v[110:113], v[78:81], v[30:33]
	v_mfma_f32_16x16x32_bf16 v[134:137], v[216:219], v[78:81], v[26:29]
	v_mfma_f32_16x16x32_bf16 v[138:141], v[110:113], v[168:171], v[14:17]
	v_mfma_f32_16x16x32_bf16 v[142:145], v[216:219], v[168:171], v[10:13]
	s_setprio 0
	s_barrier
	s_nop 0
	ds_read_b128 v[10:13], v150 offset:32768
	ds_read_b128 v[14:17], v150 offset:33792
	ds_read_b128 v[164:167], v150 offset:34816
	ds_read_b128 v[168:171], v150 offset:35840
	ds_read_b128 v[26:29], v149 offset:32768
	ds_read_b128 v[30:33], v149 offset:33792
	ds_read_b128 v[42:45], v149 offset:34816
	ds_read_b128 v[46:49], v149 offset:35840
	ds_read_b128 v[172:175], v149 offset:36864
	ds_read_b128 v[176:179], v149 offset:37888
	ds_read_b128 v[212:215], v149 offset:38912
	ds_read_b128 v[216:219], v149 offset:39936
	s_waitcnt vmcnt(2)
	s_barrier
	s_waitcnt lgkmcnt(0)
	s_setprio 1
	s_waitcnt lgkmcnt(0)
	v_mfma_f32_16x16x32_bf16 v[74:77], v[10:13], v[26:29], v[126:129]
	v_mfma_f32_16x16x32_bf16 v[126:129], v[14:17], v[30:33], v[74:77]
	v_mfma_f32_16x16x32_bf16 v[74:77], v[164:167], v[26:29], v[122:125]
	v_mfma_f32_16x16x32_bf16 v[122:125], v[168:171], v[30:33], v[74:77]
	v_mfma_f32_16x16x32_bf16 v[74:77], v[10:13], v[42:45], v[118:121]
	v_mfma_f32_16x16x32_bf16 v[110:113], v[14:17], v[46:49], v[74:77]
	v_mfma_f32_16x16x32_bf16 v[74:77], v[164:167], v[42:45], v[114:117]
	v_mfma_f32_16x16x32_bf16 v[106:109], v[168:171], v[46:49], v[74:77]
	v_mfma_f32_16x16x32_bf16 v[74:77], v[10:13], v[172:175], v[184:187]
	v_mfma_f32_16x16x32_bf16 v[94:97], v[14:17], v[176:179], v[74:77]
	v_mfma_f32_16x16x32_bf16 v[74:77], v[164:167], v[172:175], v[188:191]
	v_mfma_f32_16x16x32_bf16 v[90:93], v[168:171], v[176:179], v[74:77]
	v_mfma_f32_16x16x32_bf16 v[74:77], v[10:13], v[212:215], v[102:105]
	v_mfma_f32_16x16x32_bf16 v[78:81], v[14:17], v[216:219], v[74:77]
	v_mfma_f32_16x16x32_bf16 v[74:77], v[164:167], v[212:215], v[98:101]
	v_mfma_f32_16x16x32_bf16 v[74:77], v[168:171], v[216:219], v[74:77]
	s_setprio 0
	s_barrier
; #define LDA8(dst, b, h) _Pragma("unroll") for (int m = 0; m < 4; ++m) _Pragma("unroll") for (int k = 0; k < 2; ++k) \
;     dst[m][k] = *(const bf16x8*)(la + ((b) * 2 + (h)) * HTB + (m * 2 + k) * 1024)
; #define LDB8(dst, b, h) _Pragma("unroll") for (int n = 0; n < 2; ++n) _Pragma("unroll") for (int k = 0; k < 2; ++k) \
;     dst[n][k] = *(const bf16x8*)(lb + ((b) * 2 + (h)) * HTB + (n * 2 + k) * 1024)
; #define MMA8(ai, bj, At_, Bt_) do { __builtin_amdgcn_s_setprio(1); \
;     _Pragma("unroll") for (int m = 0; m < 4; ++m) _Pragma("unroll") for (int n = 0; n < 2; ++n) _Pragma("unroll") for (int k = 0; k < 2; ++k) \
;       acc[ai][bj][m][n] = __builtin_amdgcn_mfma_f32_16x16x32_bf16(Bt_[n][k], At_[m][k], acc[ai][bj][m][n], 0, 0, 0); \
;     __builtin_amdgcn_s_setprio(0); } while (0)
; #define WAIT_V8(n) asm volatile("s_waitcnt vmcnt(" #n ")" ::: "memory")
; #define WAIT_L8(n) asm volatile("s_waitcnt lgkmcnt(" #n ")" ::: "memory")
; #define BAR8 __builtin_amdgcn_s_barrier()
; DI void gemm8p(const bf16_t* __restrict__ A, const bf16_t* __restrict__ Bt, int K, f32x4v (&acc)[2][2][4][2], char* smem) {
;     ...
;   { LDB8(B0, 1, 0); LDA8(At, 1, 0); WAIT_V8(2); BAR8; WAIT_L8(0); MMA8(0, 0, At, B0); BAR8;
;     LDB8(B1, 1, 1); WAIT_V8(0); BAR8; WAIT_L8(0); MMA8(0, 1, At, B1); BAR8;
;     LDA8(At, 1, 1); BAR8; WAIT_L8(0); MMA8(1, 0, At, B0); MMA8(1, 1, At, B1); BAR8; }
;   if (wr == 0) BAR8;
;   asm volatile("s_waitcnt lgkmcnt(0)" ::: "memory");
;   BAR8;
	ds_read_b128 v[184:187], v150 offset:49152
	ds_read_b128 v[188:191], v150 offset:50176
	ds_read_b128 v[228:231], v150 offset:51200
	ds_read_b128 v[232:235], v150 offset:52224
	s_waitcnt vmcnt(0)
	s_barrier
	s_waitcnt lgkmcnt(0)
	s_setprio 1
	s_waitcnt lgkmcnt(0)
	v_mfma_f32_16x16x32_bf16 v[98:101], v[184:187], v[26:29], v[220:223]
	v_mfma_f32_16x16x32_bf16 v[26:29], v[228:231], v[26:29], v[152:155]
	v_mfma_f32_16x16x32_bf16 v[114:117], v[232:235], v[30:33], v[26:29]
	v_mfma_f32_16x16x32_bf16 v[26:29], v[184:187], v[42:45], v[86:89]
	v_mfma_f32_16x16x32_bf16 v[102:105], v[188:191], v[46:49], v[26:29]
	v_mfma_f32_16x16x32_bf16 v[26:29], v[228:231], v[42:45], v[82:85]
	v_mfma_f32_16x16x32_bf16 v[118:121], v[188:191], v[30:33], v[98:101]
	v_mfma_f32_16x16x32_bf16 v[98:101], v[232:235], v[46:49], v[26:29]
	v_mfma_f32_16x16x32_bf16 v[26:29], v[184:187], v[172:175], v[156:159]
	v_mfma_f32_16x16x32_bf16 v[86:89], v[188:191], v[176:179], v[26:29]
	v_mfma_f32_16x16x32_bf16 v[26:29], v[228:231], v[172:175], v[160:163]
	v_mfma_f32_16x16x32_bf16 v[82:85], v[232:235], v[176:179], v[26:29]
	v_mfma_f32_16x16x32_bf16 v[26:29], v[184:187], v[212:215], v[70:73]
	v_mfma_f32_16x16x32_bf16 v[70:73], v[188:191], v[216:219], v[26:29]
	v_mfma_f32_16x16x32_bf16 v[26:29], v[228:231], v[212:215], v[66:69]
	v_mfma_f32_16x16x32_bf16 v[66:69], v[232:235], v[216:219], v[26:29]
	s_setprio 0
	s_barrier
	ds_read_b128 v[150:153], v149 offset:49152
	ds_read_b128 v[154:157], v149 offset:50176
	ds_read_b128 v[158:161], v149 offset:51200
	ds_read_b128 v[172:175], v149 offset:52224
	ds_read_b128 v[176:179], v149 offset:53248
	ds_read_b128 v[212:215], v149 offset:54272
	ds_read_b128 v[216:219], v149 offset:55296
	ds_read_b128 v[220:223], v149 offset:56320
	s_barrier
	s_waitcnt lgkmcnt(0)
	s_setprio 1
	s_waitcnt lgkmcnt(0)
	v_mfma_f32_16x16x32_bf16 v[26:29], v[10:13], v[150:153], v[62:65]
	v_mfma_f32_16x16x32_bf16 v[62:65], v[14:17], v[154:157], v[26:29]
	v_mfma_f32_16x16x32_bf16 v[26:29], v[164:167], v[150:153], v[58:61]
	v_mfma_f32_16x16x32_bf16 v[58:61], v[168:171], v[154:157], v[26:29]
	v_mfma_f32_16x16x32_bf16 v[26:29], v[10:13], v[158:161], v[54:57]
	v_mfma_f32_16x16x32_bf16 v[46:49], v[14:17], v[172:175], v[26:29]
	v_mfma_f32_16x16x32_bf16 v[26:29], v[164:167], v[158:161], v[50:53]
	v_mfma_f32_16x16x32_bf16 v[42:45], v[168:171], v[172:175], v[26:29]
	v_mfma_f32_16x16x32_bf16 v[26:29], v[10:13], v[176:179], v[180:183]
	v_mfma_f32_16x16x32_bf16 v[10:13], v[10:13], v[216:219], v[38:41]
	v_mfma_f32_16x16x32_bf16 v[30:33], v[14:17], v[212:215], v[26:29]
	v_mfma_f32_16x16x32_bf16 v[26:29], v[164:167], v[176:179], v[224:227]
	v_mfma_f32_16x16x32_bf16 v[14:17], v[14:17], v[220:223], v[10:13]
	v_mfma_f32_16x16x32_bf16 v[10:13], v[164:167], v[216:219], v[34:37]
	v_mfma_f32_16x16x32_bf16 v[26:29], v[168:171], v[212:215], v[26:29]
	v_mfma_f32_16x16x32_bf16 v[10:13], v[168:171], v[220:223], v[10:13]
	s_setprio 0
	s_setprio 1
	v_mfma_f32_16x16x32_bf16 v[34:37], v[184:187], v[150:153], v[130:133]
	v_mfma_f32_16x16x32_bf16 v[54:57], v[188:191], v[154:157], v[34:37]
	v_mfma_f32_16x16x32_bf16 v[34:37], v[228:231], v[150:153], v[134:137]
	v_mfma_f32_16x16x32_bf16 v[18:21], v[228:231], v[158:161], v[18:21]
	v_mfma_f32_16x16x32_bf16 v[50:53], v[232:235], v[154:157], v[34:37]
	v_mfma_f32_16x16x32_bf16 v[22:25], v[184:187], v[158:161], v[22:25]
	v_mfma_f32_16x16x32_bf16 v[34:37], v[232:235], v[172:175], v[18:21]
	v_mfma_f32_16x16x32_bf16 v[18:21], v[184:187], v[176:179], v[138:141]
	v_mfma_f32_16x16x32_bf16 v[38:41], v[188:191], v[172:175], v[22:25]
	v_mfma_f32_16x16x32_bf16 v[22:25], v[188:191], v[212:215], v[18:21]
	v_mfma_f32_16x16x32_bf16 v[18:21], v[228:231], v[176:179], v[142:145]
	v_mfma_f32_16x16x32_bf16 v[6:9], v[184:187], v[216:219], v[6:9]
	v_mfma_f32_16x16x32_bf16 v[2:5], v[228:231], v[216:219], v[2:5]
	v_mfma_f32_16x16x32_bf16 v[18:21], v[232:235], v[212:215], v[18:21]
	v_mfma_f32_16x16x32_bf16 v[6:9], v[188:191], v[220:223], v[6:9]
	v_mfma_f32_16x16x32_bf16 v[2:5], v[232:235], v[220:223], v[2:5]
	s_setprio 0
	s_movk_i32 s0, 0x100
	v_cmp_gt_u32_e32 vcc, s0, v148
	s_barrier
	s_and_saveexec_b64 s[0:1], vcc
	s_cbranch_execz .LBB0_467
	s_barrier
